# sample-attention loop: second register staging set, unrolled by 2, two K/V tiles of loads in flight
# baseline (speedup 1.0000x reference)
; #define LAS __attribute__((address_space(3)))
; DI unsigned cvtpk(float lo, float hi) { f32x2_t v = {lo, hi}; bf16x2_t b = __builtin_convertvector(v, bf16x2_t); return __builtin_bit_cast(unsigned, b); }
; DI void attn_unit(const Params& p, LAS unsigned char* ldsu, int kind, int b, int h, int u, float lam) {
;     ...
;         f32x4 kr[4], vr[4];
;         auto ld = [&](int t) {
;             const float *ks, *vs; int nv = 64;
;             if (t == 0) { ks = p.cache_k + ((size_t)b * LCACHE + 4096) * 512 + hc; vs = p.cache_v + ((size_t)b * LCACHE + 4096) * 512 + hc; nv = 16; }
;             else if (t < 65) { ks = p.cache_k + ((size_t)b * LCACHE + 64 * (t - 1)) * 512 + hc; vs = p.cache_v + ((size_t)b * LCACHE + 64 * (t - 1)) * 512 + hc; }
;             else { ks = p.out + O_KS + (size_t)b * DSEQ * 512 + hc; vs = p.out + O_VS + (size_t)b * DSEQ * 512 + hc; }
; #pragma unroll
;             for (int j = 0; j < 4; ++j) { const int pc = tid + 512 * j, rr = pc >> 5, c4 = pc & 31;
;                 kr[j] = (f32x4){0.f, 0.f, 0.f, 0.f}; vr[j] = (f32x4){0.f, 0.f, 0.f, 0.f};
;                 if (rr < nv) { kr[j] = *(const f32x4*)(ks + (size_t)rr * 512 + c4 * 4); vr[j] = *(const f32x4*)(vs + (size_t)rr * 512 + c4 * 4); } }
;         };
;         auto st = [&](int t) { LAS char* sp = lds + (t & 1) * SLOT_B;
; #pragma unroll
;             for (int j = 0; j < 4; ++j) { const int pc = tid + 512 * j, rr = pc >> 5, c4 = pc & 31;
;                 u32x2 kw, vw; kw.x = cvtpk(kr[j][0], kr[j][1]); kw.y = cvtpk(kr[j][2], kr[j][3]); vw.x = cvtpk(vr[j][0], vr[j][1]); vw.y = cvtpk(vr[j][2], vr[j][3]);
;                 *(LAS u32x2*)(sp + rr * KRS + c4 * 8) = kw; *(LAS u32x2*)(sp + SLOT_V + rr * VRS + c4 * 8) = vw; } };
;         ld(0); st(0); ld(1);
;         __syncthreads();
;         for (int t = 0; t < ntl; ++t) {
.LBB0_703:
	s_or_b64 exec, exec, s[12:13]
	s_mov_b32 s17, s63
	s_lshl_b64 s[12:13], s[16:17], 17
	v_readlane_b32 s0, v254, 18
	s_add_u32 s0, s0, s12
	v_readlane_b32 s1, v254, 19
	s_addc_u32 s1, s1, s13
	v_readlane_b32 s17, v254, 20
	s_add_u32 s12, s17, s12
	v_readlane_b32 s17, v254, 21
	s_addc_u32 s13, s17, s13
	s_mul_i32 s20, s16, 0x808000
	v_readlane_b32 s18, v254, 26
	s_mul_hi_u32 s17, s16, 0x808000
	s_add_u32 s18, s18, s20
	v_readlane_b32 s19, v254, 27
	v_lshlrev_b64 v[20:21], 9, v[34:35]
	v_lshlrev_b64 v[22:23], 9, v[36:37]
	v_lshlrev_b64 v[24:25], 9, v[38:39]
	s_addc_u32 s19, s19, s17
	v_readlane_b32 s21, v254, 28
	v_mov_b32_e32 v14, v1
	v_mov_b32_e32 v15, v1
	v_mul_lo_u32 v202, v34, s83
	v_mul_lo_u32 v201, v36, s83
	v_mul_lo_u32 v200, v38, s83
	v_mul_lo_u32 v199, v40, s83
	s_add_u32 s20, s21, s20
	v_readlane_b32 s21, v254, 29
	v_mov_b32_e32 v0, v1
	v_mov_b32_e32 v2, v1
	v_mov_b32_e32 v3, v1
	v_mov_b32_e32 v4, v1
	v_mov_b32_e32 v5, v1
	v_mov_b32_e32 v6, v1
	v_mov_b32_e32 v7, v1
	v_mov_b32_e32 v8, v1
	v_mov_b32_e32 v9, v1
	v_mov_b32_e32 v10, v1
	v_mov_b32_e32 v11, v1
	v_mov_b32_e32 v12, v1
	v_mov_b32_e32 v13, v1
	v_lshlrev_b64 v[160:161], 2, v[20:21]
	v_lshlrev_b64 v[162:163], 2, v[22:23]
	v_lshlrev_b64 v[164:165], 2, v[24:25]
	v_lshlrev_b64 v[166:167], 2, v[16:17]
	v_lshlrev_b64 v[168:169], 2, v[18:19]
	v_mov_b64_e32 v[30:31], v[14:15]
	v_mov_b64_e32 v[46:47], v[14:15]
	v_mov_b64_e32 v[62:63], v[14:15]
	v_mov_b64_e32 v[78:79], v[14:15]
	v_add3_u32 v198, v176, v177, v178
	s_addc_u32 s21, s21, s17
	s_add_i32 s17, s31, -2
	s_mov_b32 s22, 0
	v_mov_b64_e32 v[28:29], v[12:13]
	v_mov_b64_e32 v[26:27], v[10:11]
	v_mov_b64_e32 v[24:25], v[8:9]
	v_mov_b64_e32 v[22:23], v[6:7]
	v_mov_b64_e32 v[20:21], v[4:5]
	v_mov_b64_e32 v[18:19], v[2:3]
	v_mov_b64_e32 v[16:17], v[0:1]
	v_mov_b64_e32 v[44:45], v[12:13]
	v_mov_b64_e32 v[42:43], v[10:11]
	v_mov_b64_e32 v[40:41], v[8:9]
	v_mov_b64_e32 v[38:39], v[6:7]
	v_mov_b64_e32 v[36:37], v[4:5]
	v_mov_b64_e32 v[34:35], v[2:3]
	v_mov_b64_e32 v[32:33], v[0:1]
	v_mov_b64_e32 v[60:61], v[12:13]
	v_mov_b64_e32 v[58:59], v[10:11]
	v_mov_b64_e32 v[56:57], v[8:9]
	v_mov_b64_e32 v[54:55], v[6:7]
	v_mov_b64_e32 v[52:53], v[4:5]
	v_mov_b64_e32 v[50:51], v[2:3]
	v_mov_b64_e32 v[48:49], v[0:1]
	v_mov_b64_e32 v[76:77], v[12:13]
	v_mov_b64_e32 v[74:75], v[10:11]
	v_mov_b64_e32 v[72:73], v[8:9]
	v_mov_b64_e32 v[70:71], v[6:7]
	v_mov_b64_e32 v[68:69], v[4:5]
	v_mov_b64_e32 v[66:67], v[2:3]
	v_mov_b64_e32 v[64:65], v[0:1]
	s_add_u32 s22, s18, s34
	s_addc_u32 s23, s19, 0
	s_add_u32 s24, s20, s34
	s_addc_u32 s25, s21, 0
	v_lshl_add_u64 v[4:5], s[22:23], 0, v[160:161]
	v_lshl_add_u64 v[2:3], s[24:25], 0, v[160:161]
	v_lshl_add_u64 v[4:5], v[4:5], 0, v[168:169]
	v_lshl_add_u64 v[2:3], v[2:3], 0, v[168:169]
	global_load_dwordx4 v[228:231], v[4:5], off
	global_load_dwordx4 v[224:227], v[2:3], off
	v_lshl_add_u64 v[4:5], s[22:23], 0, v[162:163]
	v_lshl_add_u64 v[2:3], s[24:25], 0, v[162:163]
	v_lshl_add_u64 v[4:5], v[4:5], 0, v[168:169]
	v_lshl_add_u64 v[2:3], v[2:3], 0, v[168:169]
	global_load_dwordx4 v[232:235], v[4:5], off
	global_load_dwordx4 v[220:223], v[2:3], off
	v_lshl_add_u64 v[4:5], s[22:23], 0, v[164:165]
	v_lshl_add_u64 v[2:3], s[24:25], 0, v[164:165]
	v_lshl_add_u64 v[4:5], v[4:5], 0, v[168:169]
	v_lshl_add_u64 v[2:3], v[2:3], 0, v[168:169]
	global_load_dwordx4 v[240:243], v[4:5], off
	global_load_dwordx4 v[236:239], v[2:3], off
	v_lshl_add_u64 v[4:5], s[22:23], 0, v[166:167]
	v_lshl_add_u64 v[2:3], s[24:25], 0, v[166:167]
	v_lshl_add_u64 v[4:5], v[4:5], 0, v[168:169]
	v_lshl_add_u64 v[2:3], v[2:3], 0, v[168:169]
	global_load_dwordx4 v[248:251], v[4:5], off
	global_load_dwordx4 v[244:247], v[2:3], off
	s_add_u32 s18, s18, 0x20000
	s_addc_u32 s19, s19, 0
	s_add_u32 s20, s20, 0x20000
	s_addc_u32 s21, s21, 0
	s_mov_b32 s22, 0
	s_waitcnt lgkmcnt(0)
	s_barrier
	s_cmp_gt_i32 s22, s29
	s_cbranch_scc1 .LBB0_706
	s_branch .LBB0_705

; #define LAS __attribute__((address_space(3)))
; DI unsigned cvtpk(float lo, float hi) { f32x2_t v = {lo, hi}; bf16x2_t b = __builtin_convertvector(v, bf16x2_t); return __builtin_bit_cast(unsigned, b); }
; DI void attn_unit(const Params& p, LAS unsigned char* ldsu, int kind, int b, int h, int u, float lam) {
;     ...
;         auto st = [&](int t) { LAS char* sp = lds + (t & 1) * SLOT_B;
; #pragma unroll
;             for (int j = 0; j < 4; ++j) { const int pc = tid + 512 * j, rr = pc >> 5, c4 = pc & 31;
;                 u32x2 kw, vw; kw.x = cvtpk(kr[j][0], kr[j][1]); kw.y = cvtpk(kr[j][2], kr[j][3]); vw.x = cvtpk(vr[j][0], vr[j][1]); vw.y = cvtpk(vr[j][2], vr[j][3]);
;                 *(LAS u32x2*)(sp + rr * KRS + c4 * 8) = kw; *(LAS u32x2*)(sp + SLOT_V + rr * VRS + c4 * 8) = vw; } };
;         ld(0); st(0); ld(1);
;         __syncthreads();
;         for (int t = 0; t < ntl; ++t) {
;             const LAS char* sp = lds + (t & 1) * SLOT_B;
;             if (t <= my_last) { bf16x8 pf[4]; attn_qk(sp + kboff, qf, pf, l); attn_pv(sp + vboff, pf, O); }
;             if (t + 1 < ntl) st(t + 1);
;             if (t + 2 < ntl) ld(t + 2);
.LBB0_706:
	s_add_i32 s37, s22, 1
	s_bitcmp1_b32 s37, 0
	s_cselect_b32 s23, 0x9400, 0
	s_add_i32 s35, s23, 0
	s_waitcnt vmcnt(9)
	v_cvt_pk_bf16_f32 v2, v136, v137
	v_cvt_pk_bf16_f32 v3, v138, v139
	v_add3_u32 v0, s35, v180, v179
	s_waitcnt vmcnt(8)
	v_cvt_pk_bf16_f32 v4, v132, v133
	v_cvt_pk_bf16_f32 v5, v134, v135
	ds_write_b64 v0, v[2:3]
	v_add3_u32 v0, s35, v202, v179
	ds_write_b64 v0, v[4:5] offset:17408
	v_cvt_pk_bf16_f32 v2, v140, v141
	v_cvt_pk_bf16_f32 v3, v142, v143
	v_add3_u32 v0, s35, v181, v179
	v_cvt_pk_bf16_f32 v4, v128, v129
	v_cvt_pk_bf16_f32 v5, v130, v131
	ds_write_b64 v0, v[2:3]
	v_add3_u32 v0, s35, v201, v179
	ds_write_b64 v0, v[4:5] offset:17408
	v_cvt_pk_bf16_f32 v2, v148, v149
	v_cvt_pk_bf16_f32 v3, v150, v151
	v_add3_u32 v0, s35, v196, v179
	v_cvt_pk_bf16_f32 v4, v144, v145
	v_cvt_pk_bf16_f32 v5, v146, v147
	ds_write_b64 v0, v[2:3]
	v_add3_u32 v0, s35, v200, v179
	ds_write_b64 v0, v[4:5] offset:17408
	v_cvt_pk_bf16_f32 v2, v156, v157
	v_cvt_pk_bf16_f32 v3, v158, v159
	v_add3_u32 v0, s35, v197, v179
	v_cvt_pk_bf16_f32 v4, v152, v153
	v_cvt_pk_bf16_f32 v5, v154, v155
	ds_write_b64 v0, v[2:3]
	v_add3_u32 v0, s35, v199, v179
	s_cmp_gt_u32 s22, 61
	s_mov_b64 s[24:25], s[12:13]
	s_mov_b64 s[22:23], s[0:1]
	ds_write_b64 v0, v[4:5] offset:17408
	s_cbranch_scc1 .LBB0_708
	s_mov_b64 s[24:25], s[20:21]
	s_mov_b64 s[22:23], s[18:19]

; #define LAS __attribute__((address_space(3)))
; DI void attn_unit(const Params& p, LAS unsigned char* ldsu, int kind, int b, int h, int u, float lam) {
;     ...
;         for (int t = 0; t < ntl; ++t) {
;             const LAS char* sp = lds + (t & 1) * SLOT_B;
;             if (t <= my_last) { bf16x8 pf[4]; attn_qk(sp + kboff, qf, pf, l); attn_pv(sp + vboff, pf, O); }
;             if (t + 1 < ntl) st(t + 1);
;             if (t + 2 < ntl) ld(t + 2);
;             asm volatile("s_waitcnt lgkmcnt(0)\n\ts_barrier" ::: "memory");
.LBB0_716:
	s_or_b64 exec, exec, s[26:27]
	s_add_u32 s18, s18, 0x20000
	s_addc_u32 s19, s19, 0
	s_add_u32 s20, s20, 0x20000
	s_waitcnt lgkmcnt(0)
	s_barrier
	s_addc_u32 s21, s21, 0
	s_mov_b32 s22, s37
	s_cmp_gt_i32 s22, s29
	s_cbranch_scc1 .Las_706b

; #define LAS __attribute__((address_space(3)))
; DI unsigned cvtpk(float lo, float hi) { f32x2_t v = {lo, hi}; bf16x2_t b = __builtin_convertvector(v, bf16x2_t); return __builtin_bit_cast(unsigned, b); }
; DI void attn_unit(const Params& p, LAS unsigned char* ldsu, int kind, int b, int h, int u, float lam) {
;     ...
;         auto ld = [&](int t) {
;             const float *ks, *vs; int nv = 64;
;             if (t == 0) { ks = p.cache_k + ((size_t)b * LCACHE + 4096) * 512 + hc; vs = p.cache_v + ((size_t)b * LCACHE + 4096) * 512 + hc; nv = 16; }
;             else if (t < 65) { ks = p.cache_k + ((size_t)b * LCACHE + 64 * (t - 1)) * 512 + hc; vs = p.cache_v + ((size_t)b * LCACHE + 64 * (t - 1)) * 512 + hc; }
;             else { ks = p.out + O_KS + (size_t)b * DSEQ * 512 + hc; vs = p.out + O_VS + (size_t)b * DSEQ * 512 + hc; }
; #pragma unroll
;             for (int j = 0; j < 4; ++j) { const int pc = tid + 512 * j, rr = pc >> 5, c4 = pc & 31;
;                 kr[j] = (f32x4){0.f, 0.f, 0.f, 0.f}; vr[j] = (f32x4){0.f, 0.f, 0.f, 0.f};
;                 if (rr < nv) { kr[j] = *(const f32x4*)(ks + (size_t)rr * 512 + c4 * 4); vr[j] = *(const f32x4*)(vs + (size_t)rr * 512 + c4 * 4); } }
;         };
;         auto st = [&](int t) { LAS char* sp = lds + (t & 1) * SLOT_B;
; #pragma unroll
;             for (int j = 0; j < 4; ++j) { const int pc = tid + 512 * j, rr = pc >> 5, c4 = pc & 31;
;                 u32x2 kw, vw; kw.x = cvtpk(kr[j][0], kr[j][1]); kw.y = cvtpk(kr[j][2], kr[j][3]); vw.x = cvtpk(vr[j][0], vr[j][1]); vw.y = cvtpk(vr[j][2], vr[j][3]);
;                 *(LAS u32x2*)(sp + rr * KRS + c4 * 8) = kw; *(LAS u32x2*)(sp + SLOT_V + rr * VRS + c4 * 8) = vw; } };
.Las_706b:
	s_add_i32 s37, s22, 1
	s_bitcmp1_b32 s37, 0
	s_cselect_b32 s23, 0x9400, 0
	s_add_i32 s35, s23, 0
	s_waitcnt vmcnt(9)
	v_cvt_pk_bf16_f32 v2, v228, v229
	v_cvt_pk_bf16_f32 v3, v230, v231
	v_add3_u32 v0, s35, v180, v179
	s_waitcnt vmcnt(8)
	v_cvt_pk_bf16_f32 v4, v224, v225
	v_cvt_pk_bf16_f32 v5, v226, v227
	ds_write_b64 v0, v[2:3]
	v_add3_u32 v0, s35, v202, v179
	ds_write_b64 v0, v[4:5] offset:17408
	v_cvt_pk_bf16_f32 v2, v232, v233
	v_cvt_pk_bf16_f32 v3, v234, v235
	v_add3_u32 v0, s35, v181, v179
	v_cvt_pk_bf16_f32 v4, v220, v221
	v_cvt_pk_bf16_f32 v5, v222, v223
	ds_write_b64 v0, v[2:3]
	v_add3_u32 v0, s35, v201, v179
	ds_write_b64 v0, v[4:5] offset:17408
	v_cvt_pk_bf16_f32 v2, v240, v241
	v_cvt_pk_bf16_f32 v3, v242, v243
	v_add3_u32 v0, s35, v196, v179
	v_cvt_pk_bf16_f32 v4, v236, v237
	v_cvt_pk_bf16_f32 v5, v238, v239
	ds_write_b64 v0, v[2:3]
	v_add3_u32 v0, s35, v200, v179
	ds_write_b64 v0, v[4:5] offset:17408
	v_cvt_pk_bf16_f32 v2, v248, v249
	v_cvt_pk_bf16_f32 v3, v250, v251
	v_add3_u32 v0, s35, v197, v179
	v_cvt_pk_bf16_f32 v4, v244, v245
	v_cvt_pk_bf16_f32 v5, v246, v247
	ds_write_b64 v0, v[2:3]
	v_add3_u32 v0, s35, v199, v179
	s_cmp_gt_u32 s22, 62
	s_mov_b64 s[24:25], s[20:21]
	s_mov_b64 s[22:23], s[18:19]
	ds_write_b64 v0, v[4:5] offset:17408
	s_cbranch_scc1 .Las_noload
.Las_708:
	s_add_u32 s22, s22, s34
	s_addc_u32 s23, s23, 0
	s_add_u32 s24, s24, s34
	s_addc_u32 s25, s25, 0
	v_mov_b32_e32 v220, 0
	v_mov_b32_e32 v224, 0
	v_mov_b32_e32 v225, 0
	v_mov_b32_e32 v226, 0
	v_mov_b32_e32 v227, 0
	v_mov_b32_e32 v228, 0
	v_mov_b32_e32 v229, 0
	v_mov_b32_e32 v230, 0
	v_mov_b32_e32 v231, 0
	s_and_saveexec_b64 s[26:27], vcc
	s_cbranch_execz .Las_710
	v_lshl_add_u64 v[4:5], s[22:23], 0, v[160:161]
	v_lshl_add_u64 v[2:3], s[24:25], 0, v[160:161]
	v_lshl_add_u64 v[4:5], v[4:5], 0, v[168:169]
	v_lshl_add_u64 v[2:3], v[2:3], 0, v[168:169]
	global_load_dwordx4 v[228:231], v[4:5], off
	global_load_dwordx4 v[224:227], v[2:3], off
.Las_710:
	s_or_b64 exec, exec, s[26:27]
	v_mov_b32_e32 v221, 0
	v_mov_b32_e32 v222, 0
	v_mov_b32_e32 v223, 0
	v_mov_b32_e32 v232, 0
	v_mov_b32_e32 v233, 0
	v_mov_b32_e32 v234, 0
	v_mov_b32_e32 v235, 0
	s_and_saveexec_b64 s[26:27], s[6:7]
	s_cbranch_execz .Las_712
	v_lshl_add_u64 v[4:5], s[22:23], 0, v[162:163]
	v_lshl_add_u64 v[2:3], s[24:25], 0, v[162:163]
	v_lshl_add_u64 v[4:5], v[4:5], 0, v[168:169]
	v_lshl_add_u64 v[2:3], v[2:3], 0, v[168:169]
	global_load_dwordx4 v[232:235], v[4:5], off
	global_load_dwordx4 v[220:223], v[2:3], off
.Las_712:
	s_or_b64 exec, exec, s[26:27]
	v_mov_b32_e32 v244, 0
	v_mov_b32_e32 v236, 0
	v_mov_b32_e32 v237, 0
	v_mov_b32_e32 v238, 0
	v_mov_b32_e32 v239, 0
	v_mov_b32_e32 v240, 0
	v_mov_b32_e32 v241, 0
	v_mov_b32_e32 v242, 0
	v_mov_b32_e32 v243, 0
	s_and_saveexec_b64 s[26:27], s[8:9]
	s_cbranch_execz .Las_714
	v_lshl_add_u64 v[4:5], s[22:23], 0, v[164:165]
	v_lshl_add_u64 v[2:3], s[24:25], 0, v[164:165]
	v_lshl_add_u64 v[4:5], v[4:5], 0, v[168:169]
	v_lshl_add_u64 v[2:3], v[2:3], 0, v[168:169]
	global_load_dwordx4 v[240:243], v[4:5], off
	global_load_dwordx4 v[236:239], v[2:3], off
.Las_714:
	s_or_b64 exec, exec, s[26:27]
	v_mov_b32_e32 v245, 0
	v_mov_b32_e32 v246, 0
	v_mov_b32_e32 v247, 0
	v_mov_b32_e32 v248, 0
	v_mov_b32_e32 v249, 0
	v_mov_b32_e32 v250, 0
	v_mov_b32_e32 v251, 0
	s_and_saveexec_b64 s[26:27], s[10:11]
	s_cbranch_execz .Las_716
	v_lshl_add_u64 v[4:5], s[22:23], 0, v[166:167]
	v_lshl_add_u64 v[2:3], s[24:25], 0, v[166:167]
	v_lshl_add_u64 v[4:5], v[4:5], 0, v[168:169]
	v_lshl_add_u64 v[2:3], v[2:3], 0, v[168:169]
	global_load_dwordx4 v[248:251], v[4:5], off
	global_load_dwordx4 v[244:247], v[2:3], off

; #define LAS __attribute__((address_space(3)))
; DI void attn_qk(const LAS char* kb, const bf16x8 (&qf)[4], bf16x8 (&pf)[4], float& l) {
;     f32x16 zero;
; #pragma unroll
;     for (int i = 0; i < 16; ++i) zero[i] = 0.f;
;     bf16x8 k0[4], k1[4];
; #pragma unroll
;     for (int s = 0; s < 4; ++s) k0[s] = *(const LAS bf16x8*)(kb + 32 * s);
; #pragma unroll
;     for (int s = 0; s < 4; ++s) k1[s] = *(const LAS bf16x8*)(kb + 32 * KRS + 32 * s);
;     f32x16 st0 = MFMA32(k0[0], qf[0], zero), st1 = MFMA32(k1[0], qf[0], zero);
; #pragma unroll
;     for (int s = 1; s < 4; ++s) { st0 = MFMA32(k0[s], qf[s], st0); st1 = MFMA32(k1[s], qf[s], st1); }
;     SGB(0x100, 8); SGB(0x008, 8);
;     float sum = 0.f;
; #pragma unroll
;     for (int i = 0; i < 16; ++i) { const float e = __builtin_amdgcn_exp2f(st0[i]); st0[i] = e; sum += e; }
;     pf[0] = pack8(st0, 0); pf[1] = pack8(st0, 1);
; #pragma unroll
;     for (int i = 0; i < 16; ++i) { const float e = __builtin_amdgcn_exp2f(st1[i]); st1[i] = e; sum += e; }
;     pf[2] = pack8(st1, 0); pf[3] = pack8(st1, 1);
;     l += sum;
; }
; DI void attn_pv(const LAS char* vb, const bf16x8 (&pf)[4], f32x16 (&O)[4]) {
;     s16x4 va[8], vc[8];
; #pragma unroll
;     for (int ks = 0; ks < 4; ++ks) { va[2 * ks] = vtr(vb + ks * 16 * VRS); va[2 * ks + 1] = vtr(vb + (ks * 16 + 8) * VRS); }
; #pragma unroll
;     for (int ks = 0; ks < 4; ++ks) { vc[2 * ks] = vtr(vb + ks * 16 * VRS + 64); vc[2 * ks + 1] = vtr(vb + (ks * 16 + 8) * VRS + 64); }
; #pragma unroll
;     for (int ks = 0; ks < 4; ++ks) O[0] = MFMA32(cat4(va[2 * ks], va[2 * ks + 1]), pf[ks], O[0]);
; #pragma unroll
;     for (int ks = 0; ks < 4; ++ks) { va[2 * ks] = vtr(vb + ks * 16 * VRS + 128); va[2 * ks + 1] = vtr(vb + (ks * 16 + 8) * VRS + 128); }
;     SGB(0x100, 16); SGB(0x008, 4); SGB(0x100, 8);
; #pragma unroll
;     for (int ks = 0; ks < 4; ++ks) O[1] = MFMA32(cat4(vc[2 * ks], vc[2 * ks + 1]), pf[ks], O[1]);
; #pragma unroll
;     for (int ks = 0; ks < 4; ++ks) { vc[2 * ks] = vtr(vb + ks * 16 * VRS + 192); vc[2 * ks + 1] = vtr(vb + (ks * 16 + 8) * VRS + 192); }
;     SGB(0x008, 4); SGB(0x100, 8);
; #pragma unroll
;     for (int ks = 0; ks < 4; ++ks) O[2] = MFMA32(cat4(va[2 * ks], va[2 * ks + 1]), pf[ks], O[2]);
;     SGB(0x008, 4);
; #pragma unroll
;     for (int ks = 0; ks < 4; ++ks) O[3] = MFMA32(cat4(vc[2 * ks], vc[2 * ks + 1]), pf[ks], O[3]);
;     SGB(0x008, 4);
.Las_noload:
	s_add_u32 s18, s18, 0x20000
	s_addc_u32 s19, s19, 0
	s_add_u32 s20, s20, 0x20000
	s_waitcnt lgkmcnt(0)
	s_barrier
	s_addc_u32 s21, s21, 0
	s_cmp_lg_u32 s17, s37
	s_cbranch_scc1 .LBB0_704
	s_add_i32 s0, s31, -3
	s_cmp_ge_i32 s0, s29
	s_cbranch_scc1 .LBB0_719
	v_add_u32_e32 v0, s35, v174
	ds_read_b128 v[2:5], v0
	ds_read_b128 v[80:83], v0 offset:8704
	ds_read_b128 v[6:9], v0 offset:32
	ds_read_b128 v[10:13], v0 offset:64
	ds_read_b128 v[160:163], v0 offset:96
	ds_read_b128 v[164:167], v0 offset:8736
	ds_read_b128 v[204:207], v0 offset:8768
	ds_read_b128 v[208:211], v0 offset:8800
	v_add_u32_e32 v0, s35, v198
	s_waitcnt lgkmcnt(7)
	v_mfma_f32_32x32x16_bf16 v[96:111], v[2:5], v[112:115], 0
	s_waitcnt lgkmcnt(6)
	v_mfma_f32_32x32x16_bf16 v[80:95], v[80:83], v[112:115], 0
	s_waitcnt lgkmcnt(5)
	v_mfma_f32_32x32x16_bf16 v[96:111], v[6:9], v[116:119], v[96:111]
	s_waitcnt lgkmcnt(2)
	v_mfma_f32_32x32x16_bf16 v[80:95], v[164:167], v[116:119], v[80:95]
	v_mfma_f32_32x32x16_bf16 v[96:111], v[10:13], v[120:123], v[96:111]
	s_waitcnt lgkmcnt(1)
	v_mfma_f32_32x32x16_bf16 v[80:95], v[204:207], v[120:123], v[80:95]
	v_mfma_f32_32x32x16_bf16 v[96:111], v[160:163], v[124:127], v[96:111]
	s_waitcnt lgkmcnt(0)
	v_mfma_f32_32x32x16_bf16 v[80:95], v[208:211], v[124:127], v[80:95]
	ds_read_b64_tr_b16 v[2:3], v0 offset:17408
	ds_read_b64_tr_b16 v[4:5], v0 offset:19968
	s_nop 7
	v_exp_f32_e32 v14, v96
	v_exp_f32_e32 v15, v97
	v_exp_f32_e32 v168, v98
	v_exp_f32_e32 v169, v99
	v_exp_f32_e32 v203, v100
	v_exp_f32_e32 v216, v101
	v_exp_f32_e32 v217, v102
	v_exp_f32_e32 v218, v103
	ds_read_b64_tr_b16 v[6:7], v0 offset:22528
	ds_read_b64_tr_b16 v[8:9], v0 offset:25088
	v_cvt_pk_bf16_f32 v96, v14, v15
	v_cvt_pk_bf16_f32 v97, v168, v169
	v_cvt_pk_bf16_f32 v98, v203, v216
	v_cvt_pk_bf16_f32 v99, v217, v218
	ds_read_b64_tr_b16 v[10:11], v0 offset:27648
	ds_read_b64_tr_b16 v[12:13], v0 offset:30208
	ds_read_b64_tr_b16 v[160:161], v0 offset:32768
	ds_read_b64_tr_b16 v[162:163], v0 offset:35328
	ds_read_b64_tr_b16 v[164:165], v0 offset:17472
	ds_read_b64_tr_b16 v[166:167], v0 offset:20032
	ds_read_b64_tr_b16 v[204:205], v0 offset:22592
	ds_read_b64_tr_b16 v[206:207], v0 offset:25152
	ds_read_b64_tr_b16 v[208:209], v0 offset:27712
	ds_read_b64_tr_b16 v[210:211], v0 offset:30272
	ds_read_b64_tr_b16 v[212:213], v0 offset:32832
	ds_read_b64_tr_b16 v[214:215], v0 offset:35392
	s_waitcnt lgkmcnt(14)
	v_mfma_f32_32x32x16_bf16 v[64:79], v[2:5], v[96:99], v[64:79]
	v_exp_f32_e32 v219, v104
	v_exp_f32_e32 v220, v105
	v_exp_f32_e32 v221, v106
	v_exp_f32_e32 v222, v107
	v_exp_f32_e32 v223, v108
	v_exp_f32_e32 v224, v109
	v_exp_f32_e32 v225, v110
	v_exp_f32_e32 v226, v111
	v_cvt_pk_bf16_f32 v100, v219, v220
	v_cvt_pk_bf16_f32 v101, v221, v222
	v_cvt_pk_bf16_f32 v102, v223, v224
	v_cvt_pk_bf16_f32 v103, v225, v226
	v_exp_f32_e32 v227, v80
	v_exp_f32_e32 v228, v81
	s_waitcnt lgkmcnt(12)
	v_mfma_f32_32x32x16_bf16 v[64:79], v[6:9], v[100:103], v[64:79]
	v_exp_f32_e32 v229, v82
	v_exp_f32_e32 v230, v83
	v_exp_f32_e32 v231, v84
	v_exp_f32_e32 v232, v85
	v_exp_f32_e32 v233, v86
	v_exp_f32_e32 v234, v87
	v_cvt_pk_bf16_f32 v2, v227, v228
	v_cvt_pk_bf16_f32 v3, v229, v230
	v_cvt_pk_bf16_f32 v4, v231, v232
	v_cvt_pk_bf16_f32 v5, v233, v234
	v_exp_f32_e32 v235, v88
	v_exp_f32_e32 v236, v89
	s_waitcnt lgkmcnt(10)
	v_mfma_f32_32x32x16_bf16 v[64:79], v[10:13], v[2:5], v[64:79]
	v_exp_f32_e32 v237, v90
	v_exp_f32_e32 v238, v91
	v_exp_f32_e32 v239, v92
	v_exp_f32_e32 v240, v93
	v_exp_f32_e32 v241, v94
	v_exp_f32_e32 v242, v95
	v_cvt_pk_bf16_f32 v6, v235, v236
	v_cvt_pk_bf16_f32 v7, v237, v238
	v_cvt_pk_bf16_f32 v8, v239, v240
	v_cvt_pk_bf16_f32 v9, v241, v242
	s_waitcnt lgkmcnt(8)
	s_nop 0
	v_mfma_f32_32x32x16_bf16 v[64:79], v[160:163], v[6:9], v[64:79]
	ds_read_b64_tr_b16 v[10:11], v0 offset:17536
	ds_read_b64_tr_b16 v[12:13], v0 offset:20096
	ds_read_b64_tr_b16 v[80:81], v0 offset:22656
	ds_read_b64_tr_b16 v[82:83], v0 offset:25216
	ds_read_b64_tr_b16 v[84:85], v0 offset:27776
	ds_read_b64_tr_b16 v[86:87], v0 offset:30336
	ds_read_b64_tr_b16 v[88:89], v0 offset:32896
	ds_read_b64_tr_b16 v[90:91], v0 offset:35456
	s_waitcnt lgkmcnt(14)
	v_mfma_f32_32x32x16_bf16 v[48:63], v[164:167], v[96:99], v[48:63]
	s_waitcnt lgkmcnt(12)
	v_mfma_f32_32x32x16_bf16 v[48:63], v[204:207], v[100:103], v[48:63]
	s_waitcnt lgkmcnt(10)
	v_mfma_f32_32x32x16_bf16 v[48:63], v[208:211], v[2:5], v[48:63]
	s_waitcnt lgkmcnt(8)
	v_mfma_f32_32x32x16_bf16 v[48:63], v[212:215], v[6:9], v[48:63]
	ds_read_b64_tr_b16 v[92:93], v0 offset:17600
	ds_read_b64_tr_b16 v[94:95], v0 offset:20160
	ds_read_b64_tr_b16 v[104:105], v0 offset:22720
	ds_read_b64_tr_b16 v[106:107], v0 offset:25280
	ds_read_b64_tr_b16 v[108:109], v0 offset:27840
	ds_read_b64_tr_b16 v[110:111], v0 offset:30400
	ds_read_b64_tr_b16 v[160:161], v0 offset:32960
	ds_read_b64_tr_b16 v[162:163], v0 offset:35520
	s_waitcnt lgkmcnt(14)
	v_mfma_f32_32x32x16_bf16 v[32:47], v[10:13], v[96:99], v[32:47]
	v_add_f32_e32 v0, 0, v14
	v_add_f32_e32 v0, v15, v0
	v_add_f32_e32 v0, v168, v0
	v_add_f32_e32 v0, v169, v0
	v_add_f32_e32 v0, v203, v0
	v_add_f32_e32 v0, v216, v0
	v_add_f32_e32 v0, v217, v0
	s_waitcnt lgkmcnt(12)
	v_mfma_f32_32x32x16_bf16 v[32:47], v[80:83], v[100:103], v[32:47]
	v_add_f32_e32 v0, v218, v0
	v_add_f32_e32 v0, v219, v0
	v_add_f32_e32 v0, v220, v0
	v_add_f32_e32 v0, v221, v0
	v_add_f32_e32 v0, v222, v0
	v_add_f32_e32 v0, v223, v0
	v_add_f32_e32 v0, v224, v0
	s_waitcnt lgkmcnt(10)
	v_mfma_f32_32x32x16_bf16 v[32:47], v[84:87], v[2:5], v[32:47]
	v_add_f32_e32 v0, v225, v0
	v_add_f32_e32 v0, v226, v0
	v_add_f32_e32 v0, v227, v0
	v_add_f32_e32 v0, v228, v0
	v_add_f32_e32 v0, v229, v0
	v_add_f32_e32 v0, v230, v0
	v_add_f32_e32 v0, v231, v0
	s_waitcnt lgkmcnt(8)
	v_mfma_f32_32x32x16_bf16 v[32:47], v[88:91], v[6:9], v[32:47]
	v_add_f32_e32 v0, v232, v0
	v_add_f32_e32 v0, v233, v0
	v_add_f32_e32 v0, v234, v0
	v_add_f32_e32 v0, v235, v0
	v_add_f32_e32 v0, v236, v0
	v_add_f32_e32 v0, v237, v0
	v_add_f32_e32 v0, v238, v0
	s_waitcnt lgkmcnt(6)
	v_mfma_f32_32x32x16_bf16 v[16:31], v[92:95], v[96:99], v[16:31]
	v_add_f32_e32 v0, v239, v0
	v_add_f32_e32 v0, v240, v0
	v_add_f32_e32 v0, v241, v0
	v_add_f32_e32 v0, v242, v0
	v_add_f32_e32 v175, v175, v0
	s_waitcnt lgkmcnt(4)
	v_mfma_f32_32x32x16_bf16 v[16:31], v[104:107], v[100:103], v[16:31]
	s_waitcnt lgkmcnt(2)
	v_mfma_f32_32x32x16_bf16 v[16:31], v[108:111], v[2:5], v[16:31]
	s_waitcnt lgkmcnt(0)
	v_mfma_f32_32x32x16_bf16 v[16:31], v[160:163], v[6:9], v[16:31]
